# GEMM: first K iteration peeled with srcC=0 on first-touch MFMAs, removes the 128 v_mov accumulator zeroing per unit
# baseline (speedup 1.0000x reference)
; #define PG8_STAGE(bufoff, gbase, voff) do { _Pragma("unroll") for (int _i = 0; _i < 2; ++_i) \
;         __builtin_amdgcn_global_load_lds((const unsigned*)((const char*)(gbase) + (voff)[_i]), (PG8_LAS unsigned*)(lds + (bufoff) + ldsw + _i * 8192), 16, 0, 0); } while (0)
; #define PG8_LDA(dst, b, h) do { _Pragma("unroll") for (int m = 0; m < 4; ++m) _Pragma("unroll") for (int k = 0; k < 2; ++k) dst[m][k] = *(const PG8_LAS bf16x8*)(lds + PG8_SA(b, h) + aoff + m * 2048 + k * 1024); } while (0)
; #define PG8_LDB(dst, b, h) do { _Pragma("unroll") for (int n = 0; n < 2; ++n) _Pragma("unroll") for (int k = 0; k < 2; ++k) dst[n][k] = *(const PG8_LAS bf16x8*)(lds + PG8_SB(b, h) + boff + n * 2048 + k * 1024); } while (0)
; #define PG8_WAIT_V(n) asm volatile("s_waitcnt vmcnt(" #n ")" ::: "memory")
; #define PG8_WAIT_L(n) asm volatile("s_waitcnt lgkmcnt(" #n ")" ::: "memory")
; #define PG8_BAR __builtin_amdgcn_s_barrier()
; template <class Epi, class Sched, bool ALIGN_EPI = false, bool SP2 = false>
; __device__ __forceinline__ void gemm_phase(PG8_LAS unsigned char* lds, const Gemm g, const Sched& S, const Epi& E) {
;     ...
;         for (int t = 0; t < nt; t += 2) {
;             const bool last = (t == nt - 2);
;             const char* a1 = cA + (size_t)(t + 1) * kstep;
;             const char* a2 = last ? nA : cA + (size_t)(t + 2) * kstep; const char* b2 = last ? nB : cB + (size_t)(t + 2) * kstep;
;             const char* a3 = a2 + kstep; const char* b3 = b2 + kstep;
;             if (last && has_next) S.a_ready(nxt);
;             if constexpr (SP2) {
;             PG8_LDB(B0, 0, 0); PG8_LDB(B1, 0, 1); PG8_SCHED; PG8_LDA(At, 0, 0); PG8_STAGE(PG8_SA(1, 1), a1 + hstep, voffA);
;             PG8_WAIT_V(8); PG8_WAIT_L(0); PG8_BAR; PG8_MMA(0, 0, At, B0); PG8_MMA(0, 1, At, B1); PG8_BAR; PG8_SCHED;
;             PG8_LDA(At, 0, 1); PG8_STAGE(PG8_SB(0, 0), b2, voffB); PG8_STAGE(PG8_SB(0, 1), b2 + hstep, voffB); PG8_STAGE(PG8_SA(0, 0), a2, voffA);
;             PG8_WAIT_V(8); PG8_WAIT_L(0); PG8_BAR; PG8_MMA(1, 0, At, B0); PG8_MMA(1, 1, At, B1); PG8_BAR; PG8_SCHED;
;     ...
; #pragma unroll
;         for (int a = 0; a < 2; ++a)
; #pragma unroll
;             for (int b = 0; b < 2; ++b)
; #pragma unroll
;                 for (int m = 0; m < 4; ++m)
; #pragma unroll
;                     for (int n = 0; n < 2; ++n) acc[a][b][m][n] = (f32x4){0.f, 0.f, 0.f, 0.f};
.LBB0_321:
	s_add_u32 s12, s16, 0x80
	s_addc_u32 s13, s17, 0
	s_add_u32 s16, s14, 0x100
	s_addc_u32 s17, s15, 0
	s_mov_b32 s14, 0
	s_waitcnt vmcnt(0)
	s_waitcnt vmcnt(0)
	s_waitcnt lgkmcnt(0)
	s_add_i32 s42, s14, 2
	s_add_u32 s43, s12, 0x80
	s_addc_u32 s15, s13, 0
	s_add_i32 s75, 0, 0x10000
	s_cmp_eq_u32 s25, s14
	s_cselect_b32 s15, s55, s15
	s_cselect_b32 s14, s54, s43
	s_cselect_b32 vcc_hi, s65, s17
	s_cselect_b32 vcc_lo, s64, s16
	s_add_i32 s43, 0, 0x14000
	v_add_u32_e32 v142, s75, v199
	v_add_u32_e32 v178, s43, v199
	ds_read_b128 v[130:133], v142
	ds_read_b128 v[134:137], v142 offset:1024
	ds_read_b128 v[138:141], v142 offset:2048
	ds_read_b128 v[142:145], v142 offset:3072
	ds_read_b128 v[170:173], v178
	ds_read_b128 v[174:177], v178 offset:1024
	ds_read_b128 v[202:205], v178 offset:2048
	ds_read_b128 v[206:209], v178 offset:3072
	v_lshl_add_u64 v[178:179], s[12:13], 0, v[166:167]
	s_add_i32 m0, s56, 0xc000
	ds_read_b128 v[210:213], v201
	ds_read_b128 v[214:217], v201 offset:1024
	ds_read_b128 v[218:221], v201 offset:2048
	ds_read_b128 v[222:225], v201 offset:3072
	ds_read_b128 v[226:229], v201 offset:4096
	ds_read_b128 v[230:233], v201 offset:5120
	ds_read_b128 v[234:237], v201 offset:6144
	ds_read_b128 v[238:241], v201 offset:7168
	global_load_lds_dwordx4 v[178:179], off
	v_lshl_add_u64 v[178:179], s[12:13], 0, v[168:169]
	s_add_i32 m0, s56, 0xe000
	s_nop 0
	global_load_lds_dwordx4 v[178:179], off
	s_waitcnt vmcnt(8)
	s_waitcnt lgkmcnt(0)
	s_barrier
	s_setprio 1
	s_waitcnt lgkmcnt(0)
	v_mfma_f32_16x16x32_bf16 v[126:129], v[130:133], v[210:213], 0
	v_mfma_f32_16x16x32_bf16 v[126:129], v[134:137], v[214:217], v[126:129]
	v_mfma_f32_16x16x32_bf16 v[122:125], v[138:141], v[210:213], 0
	v_mfma_f32_16x16x32_bf16 v[122:125], v[142:145], v[214:217], v[122:125]
	v_mfma_f32_16x16x32_bf16 v[110:113], v[130:133], v[218:221], 0
	v_mfma_f32_16x16x32_bf16 v[110:113], v[134:137], v[222:225], v[110:113]
	v_mfma_f32_16x16x32_bf16 v[106:109], v[138:141], v[218:221], 0
	v_mfma_f32_16x16x32_bf16 v[106:109], v[142:145], v[222:225], v[106:109]
	v_mfma_f32_16x16x32_bf16 v[94:97], v[130:133], v[226:229], 0
	v_mfma_f32_16x16x32_bf16 v[94:97], v[134:137], v[230:233], v[94:97]
	v_mfma_f32_16x16x32_bf16 v[90:93], v[138:141], v[226:229], 0
	v_mfma_f32_16x16x32_bf16 v[90:93], v[142:145], v[230:233], v[90:93]
	v_mfma_f32_16x16x32_bf16 v[78:81], v[130:133], v[234:237], 0
	v_mfma_f32_16x16x32_bf16 v[78:81], v[134:137], v[238:241], v[78:81]
	v_mfma_f32_16x16x32_bf16 v[74:77], v[138:141], v[234:237], 0
	v_mfma_f32_16x16x32_bf16 v[74:77], v[142:145], v[238:241], v[74:77]
	s_setprio 0
	s_setprio 1
	v_mfma_f32_16x16x32_bf16 v[118:121], v[170:173], v[210:213], 0
	v_mfma_f32_16x16x32_bf16 v[118:121], v[174:177], v[214:217], v[118:121]
	v_mfma_f32_16x16x32_bf16 v[114:117], v[202:205], v[210:213], 0
	v_mfma_f32_16x16x32_bf16 v[114:117], v[206:209], v[214:217], v[114:117]
	v_mfma_f32_16x16x32_bf16 v[102:105], v[170:173], v[218:221], 0
	v_mfma_f32_16x16x32_bf16 v[102:105], v[174:177], v[222:225], v[102:105]
	v_mfma_f32_16x16x32_bf16 v[98:101], v[202:205], v[218:221], 0
	v_mfma_f32_16x16x32_bf16 v[98:101], v[206:209], v[222:225], v[98:101]
	v_mfma_f32_16x16x32_bf16 v[86:89], v[170:173], v[226:229], 0
	v_mfma_f32_16x16x32_bf16 v[86:89], v[174:177], v[230:233], v[86:89]
	v_mfma_f32_16x16x32_bf16 v[82:85], v[202:205], v[226:229], 0
	v_mfma_f32_16x16x32_bf16 v[82:85], v[206:209], v[230:233], v[82:85]
	v_mfma_f32_16x16x32_bf16 v[70:73], v[170:173], v[234:237], 0
	v_mfma_f32_16x16x32_bf16 v[70:73], v[174:177], v[238:241], v[70:73]
	v_mfma_f32_16x16x32_bf16 v[66:69], v[202:205], v[234:237], 0
	v_mfma_f32_16x16x32_bf16 v[66:69], v[206:209], v[238:241], v[66:69]
	s_setprio 0
	s_barrier
	s_add_i32 s75, s75, s23
	v_lshl_add_u64 v[178:179], vcc, 0, v[0:1]
	s_mov_b32 m0, s75
	ds_read_b128 v[210:213], v201 offset:16384
	ds_read_b128 v[214:217], v201 offset:17408
	ds_read_b128 v[218:221], v201 offset:18432
	ds_read_b128 v[222:225], v201 offset:19456
	ds_read_b128 v[226:229], v201 offset:20480
	ds_read_b128 v[230:233], v201 offset:21504
	ds_read_b128 v[234:237], v201 offset:22528
	ds_read_b128 v[238:241], v201 offset:23552
	global_load_lds_dwordx4 v[178:179], off
	s_add_i32 m0, s75, 0x2000
	v_lshl_add_u64 v[242:243], vcc, 0, v[162:163]
	s_add_u32 vcc_lo, vcc_lo, s84
	s_addc_u32 vcc_hi, vcc_hi, 0
	s_add_i32 s43, s43, s23
	global_load_lds_dwordx4 v[242:243], off
	v_lshl_add_u64 v[244:245], vcc, 0, v[0:1]
	s_mov_b32 m0, s43
	v_lshl_add_u64 v[246:247], vcc, 0, v[162:163]
	global_load_lds_dwordx4 v[244:245], off
	s_add_i32 m0, s43, 0x2000
	v_lshl_add_u64 v[248:249], s[14:15], 0, v[158:159]
	global_load_lds_dwordx4 v[246:247], off
	s_mov_b32 m0, s56
	v_lshl_add_u64 v[250:251], s[14:15], 0, v[160:161]
	global_load_lds_dwordx4 v[248:249], off
	s_mov_b32 m0, s82
	s_nop 0
	global_load_lds_dwordx4 v[250:251], off
	s_waitcnt vmcnt(8)
	s_waitcnt lgkmcnt(0)
	s_barrier
; #define PG8_STAGE(bufoff, gbase, voff) do { _Pragma("unroll") for (int _i = 0; _i < 2; ++_i) \
;         __builtin_amdgcn_global_load_lds((const unsigned*)((const char*)(gbase) + (voff)[_i]), (PG8_LAS unsigned*)(lds + (bufoff) + ldsw + _i * 8192), 16, 0, 0); } while (0)
; #define PG8_LDA(dst, b, h) do { _Pragma("unroll") for (int m = 0; m < 4; ++m) _Pragma("unroll") for (int k = 0; k < 2; ++k) dst[m][k] = *(const PG8_LAS bf16x8*)(lds + PG8_SA(b, h) + aoff + m * 2048 + k * 1024); } while (0)
; #define PG8_LDB(dst, b, h) do { _Pragma("unroll") for (int n = 0; n < 2; ++n) _Pragma("unroll") for (int k = 0; k < 2; ++k) dst[n][k] = *(const PG8_LAS bf16x8*)(lds + PG8_SB(b, h) + boff + n * 2048 + k * 1024); } while (0)
; #define PG8_MMA(ai, bj, At, Bt) do { __builtin_amdgcn_s_setprio(1); _Pragma("unroll") for (int m = 0; m < 4; ++m) _Pragma("unroll") for (int n = 0; n < 2; ++n) _Pragma("unroll") for (int k = 0; k < 2; ++k) \
;         acc[ai][bj][m][n] = __builtin_amdgcn_mfma_f32_16x16x32_bf16(Bt[n][k], At[m][k], acc[ai][bj][m][n], 0, 0, 0); __builtin_amdgcn_s_setprio(0); } while (0)
; #define PG8_WAIT_V(n) asm volatile("s_waitcnt vmcnt(" #n ")" ::: "memory")
; #define PG8_WAIT_L(n) asm volatile("s_waitcnt lgkmcnt(" #n ")" ::: "memory")
; #define PG8_BAR __builtin_amdgcn_s_barrier()
; #define PG8_SCHED __builtin_amdgcn_sched_barrier(0)
; template <class Epi, class Sched, bool ALIGN_EPI = false, bool SP2 = false>
; __device__ __forceinline__ void gemm_phase(PG8_LAS unsigned char* lds, const Gemm g, const Sched& S, const Epi& E) {
;     ...
;             PG8_WAIT_V(8); PG8_WAIT_L(0); PG8_BAR; PG8_MMA(1, 0, At, B0); PG8_MMA(1, 1, At, B1); PG8_BAR; PG8_SCHED;
;             PG8_LDB(B0, 1, 0); PG8_LDB(B1, 1, 1); PG8_SCHED; PG8_LDA(At, 1, 0); PG8_STAGE(PG8_SA(0, 1), a2 + hstep, voffA);
;             PG8_WAIT_V(8); PG8_WAIT_L(0); PG8_BAR; PG8_MMA(0, 0, At, B0); PG8_MMA(0, 1, At, B1); PG8_BAR; PG8_SCHED;
	s_setprio 1
	s_waitcnt lgkmcnt(0)
	v_mfma_f32_16x16x32_bf16 v[62:65], v[130:133], v[210:213], 0
	v_mfma_f32_16x16x32_bf16 v[62:65], v[134:137], v[214:217], v[62:65]
	v_mfma_f32_16x16x32_bf16 v[58:61], v[138:141], v[210:213], 0
	v_mfma_f32_16x16x32_bf16 v[58:61], v[142:145], v[214:217], v[58:61]
	v_mfma_f32_16x16x32_bf16 v[46:49], v[130:133], v[218:221], 0
	v_mfma_f32_16x16x32_bf16 v[46:49], v[134:137], v[222:225], v[46:49]
	v_mfma_f32_16x16x32_bf16 v[42:45], v[138:141], v[218:221], 0
	v_mfma_f32_16x16x32_bf16 v[42:45], v[142:145], v[222:225], v[42:45]
	v_mfma_f32_16x16x32_bf16 v[30:33], v[130:133], v[226:229], 0
	v_mfma_f32_16x16x32_bf16 v[30:33], v[134:137], v[230:233], v[30:33]
	v_mfma_f32_16x16x32_bf16 v[26:29], v[138:141], v[226:229], 0
	v_mfma_f32_16x16x32_bf16 v[26:29], v[142:145], v[230:233], v[26:29]
	v_mfma_f32_16x16x32_bf16 v[14:17], v[130:133], v[234:237], 0
	v_mfma_f32_16x16x32_bf16 v[14:17], v[134:137], v[238:241], v[14:17]
	v_mfma_f32_16x16x32_bf16 v[10:13], v[138:141], v[234:237], 0
	v_mfma_f32_16x16x32_bf16 v[10:13], v[142:145], v[238:241], v[10:13]
	s_setprio 0
	s_setprio 1
	v_mfma_f32_16x16x32_bf16 v[54:57], v[170:173], v[210:213], 0
	v_mfma_f32_16x16x32_bf16 v[54:57], v[174:177], v[214:217], v[54:57]
	v_mfma_f32_16x16x32_bf16 v[50:53], v[202:205], v[210:213], 0
	v_mfma_f32_16x16x32_bf16 v[50:53], v[206:209], v[214:217], v[50:53]
	v_mfma_f32_16x16x32_bf16 v[38:41], v[170:173], v[218:221], 0
	v_mfma_f32_16x16x32_bf16 v[38:41], v[174:177], v[222:225], v[38:41]
	v_mfma_f32_16x16x32_bf16 v[34:37], v[202:205], v[218:221], 0
	v_mfma_f32_16x16x32_bf16 v[34:37], v[206:209], v[222:225], v[34:37]
	v_mfma_f32_16x16x32_bf16 v[22:25], v[170:173], v[226:229], 0
	v_mfma_f32_16x16x32_bf16 v[22:25], v[174:177], v[230:233], v[22:25]
	v_mfma_f32_16x16x32_bf16 v[18:21], v[202:205], v[226:229], 0
	v_mfma_f32_16x16x32_bf16 v[18:21], v[206:209], v[230:233], v[18:21]
	v_mfma_f32_16x16x32_bf16 v[6:9], v[170:173], v[234:237], 0
	v_mfma_f32_16x16x32_bf16 v[6:9], v[174:177], v[238:241], v[6:9]
	v_mfma_f32_16x16x32_bf16 v[2:5], v[202:205], v[234:237], 0
	v_mfma_f32_16x16x32_bf16 v[2:5], v[206:209], v[238:241], v[2:5]
	s_setprio 0
	s_barrier
	s_add_i32 s43, 0, 0x18000
	s_add_i32 s75, 0, 0x1c000
	v_add_u32_e32 v142, s43, v199
	v_add_u32_e32 v206, s75, v199
	ds_read_b128 v[130:133], v142
	ds_read_b128 v[134:137], v142 offset:1024
	ds_read_b128 v[138:141], v142 offset:2048
	ds_read_b128 v[142:145], v142 offset:3072
	ds_read_b128 v[170:173], v206
	ds_read_b128 v[174:177], v206 offset:1024
	ds_read_b128 v[202:205], v206 offset:2048
	ds_read_b128 v[206:209], v206 offset:3072
	s_add_u32 s14, s14, s84
	s_addc_u32 s15, s15, 0
	s_mov_b32 m0, s83
	v_lshl_add_u64 v[252:253], s[14:15], 0, v[158:159]
	ds_read_b128 v[210:213], v201 offset:32768
	ds_read_b128 v[214:217], v201 offset:33792
	ds_read_b128 v[218:221], v201 offset:34816
	ds_read_b128 v[222:225], v201 offset:35840
	ds_read_b128 v[226:229], v201 offset:36864
	ds_read_b128 v[230:233], v201 offset:37888
	ds_read_b128 v[234:237], v201 offset:38912
	ds_read_b128 v[238:241], v201 offset:39936
	global_load_lds_dwordx4 v[252:253], off
	v_lshl_add_u64 v[252:253], s[14:15], 0, v[160:161]
	s_mov_b32 m0, s24
	s_nop 0
	global_load_lds_dwordx4 v[252:253], off
	s_waitcnt vmcnt(8)
	s_waitcnt lgkmcnt(0)
	s_barrier
	s_setprio 1
	s_waitcnt lgkmcnt(0)
	v_mfma_f32_16x16x32_bf16 v[126:129], v[130:133], v[210:213], v[126:129]
	v_mfma_f32_16x16x32_bf16 v[126:129], v[134:137], v[214:217], v[126:129]
	v_mfma_f32_16x16x32_bf16 v[122:125], v[138:141], v[210:213], v[122:125]
	v_mfma_f32_16x16x32_bf16 v[122:125], v[142:145], v[214:217], v[122:125]
	v_mfma_f32_16x16x32_bf16 v[110:113], v[130:133], v[218:221], v[110:113]
	v_mfma_f32_16x16x32_bf16 v[110:113], v[134:137], v[222:225], v[110:113]
	v_mfma_f32_16x16x32_bf16 v[106:109], v[138:141], v[218:221], v[106:109]
	v_mfma_f32_16x16x32_bf16 v[106:109], v[142:145], v[222:225], v[106:109]
	v_mfma_f32_16x16x32_bf16 v[94:97], v[130:133], v[226:229], v[94:97]
	v_mfma_f32_16x16x32_bf16 v[94:97], v[134:137], v[230:233], v[94:97]
	v_mfma_f32_16x16x32_bf16 v[90:93], v[138:141], v[226:229], v[90:93]
	v_mfma_f32_16x16x32_bf16 v[90:93], v[142:145], v[230:233], v[90:93]
	v_mfma_f32_16x16x32_bf16 v[78:81], v[130:133], v[234:237], v[78:81]
	v_mfma_f32_16x16x32_bf16 v[78:81], v[134:137], v[238:241], v[78:81]
	v_mfma_f32_16x16x32_bf16 v[74:77], v[138:141], v[234:237], v[74:77]
	v_mfma_f32_16x16x32_bf16 v[74:77], v[142:145], v[238:241], v[74:77]
	s_setprio 0
	s_setprio 1
	v_mfma_f32_16x16x32_bf16 v[118:121], v[170:173], v[210:213], v[118:121]
	v_mfma_f32_16x16x32_bf16 v[118:121], v[174:177], v[214:217], v[118:121]
	v_mfma_f32_16x16x32_bf16 v[114:117], v[202:205], v[210:213], v[114:117]
	v_mfma_f32_16x16x32_bf16 v[114:117], v[206:209], v[214:217], v[114:117]
	v_mfma_f32_16x16x32_bf16 v[102:105], v[170:173], v[218:221], v[102:105]
	v_mfma_f32_16x16x32_bf16 v[102:105], v[174:177], v[222:225], v[102:105]
	v_mfma_f32_16x16x32_bf16 v[98:101], v[202:205], v[218:221], v[98:101]
	v_mfma_f32_16x16x32_bf16 v[98:101], v[206:209], v[222:225], v[98:101]
	v_mfma_f32_16x16x32_bf16 v[86:89], v[170:173], v[226:229], v[86:89]
	v_mfma_f32_16x16x32_bf16 v[86:89], v[174:177], v[230:233], v[86:89]
	v_mfma_f32_16x16x32_bf16 v[82:85], v[202:205], v[226:229], v[82:85]
	v_mfma_f32_16x16x32_bf16 v[82:85], v[206:209], v[230:233], v[82:85]
	v_mfma_f32_16x16x32_bf16 v[70:73], v[170:173], v[234:237], v[70:73]
	v_mfma_f32_16x16x32_bf16 v[70:73], v[174:177], v[238:241], v[70:73]
	v_mfma_f32_16x16x32_bf16 v[66:69], v[202:205], v[234:237], v[66:69]
	v_mfma_f32_16x16x32_bf16 v[66:69], v[206:209], v[238:241], v[66:69]
	s_setprio 0
	s_barrier
; #define PG8_STAGE(bufoff, gbase, voff) do { _Pragma("unroll") for (int _i = 0; _i < 2; ++_i) \
;         __builtin_amdgcn_global_load_lds((const unsigned*)((const char*)(gbase) + (voff)[_i]), (PG8_LAS unsigned*)(lds + (bufoff) + ldsw + _i * 8192), 16, 0, 0); } while (0)
; #define PG8_LDA(dst, b, h) do { _Pragma("unroll") for (int m = 0; m < 4; ++m) _Pragma("unroll") for (int k = 0; k < 2; ++k) dst[m][k] = *(const PG8_LAS bf16x8*)(lds + PG8_SA(b, h) + aoff + m * 2048 + k * 1024); } while (0)
; #define PG8_MMA(ai, bj, At, Bt) do { __builtin_amdgcn_s_setprio(1); _Pragma("unroll") for (int m = 0; m < 4; ++m) _Pragma("unroll") for (int n = 0; n < 2; ++n) _Pragma("unroll") for (int k = 0; k < 2; ++k) \
;         acc[ai][bj][m][n] = __builtin_amdgcn_mfma_f32_16x16x32_bf16(Bt[n][k], At[m][k], acc[ai][bj][m][n], 0, 0, 0); __builtin_amdgcn_s_setprio(0); } while (0)
; #define PG8_WAIT_V(n) asm volatile("s_waitcnt vmcnt(" #n ")" ::: "memory")
; #define PG8_WAIT_L(n) asm volatile("s_waitcnt lgkmcnt(" #n ")" ::: "memory")
; #define PG8_BAR __builtin_amdgcn_s_barrier()
; #define PG8_SCHED __builtin_amdgcn_sched_barrier(0)
; template <class Epi, class Sched, bool ALIGN_EPI = false, bool SP2 = false>
; __device__ __forceinline__ void gemm_phase(PG8_LAS unsigned char* lds, const Gemm g, const Sched& S, const Epi& E) {
;     ...
;         for (int t = 0; t < nt; t += 2) {
;     ...
;             PG8_LDA(At, 1, 1); PG8_STAGE(PG8_SB(1, 0), b3, voffB); PG8_STAGE(PG8_SB(1, 1), b3 + hstep, voffB); PG8_STAGE(PG8_SA(1, 0), a3, voffA);
;             PG8_WAIT_V(8); PG8_WAIT_L(0); PG8_BAR; PG8_MMA(1, 0, At, B0); PG8_MMA(1, 1, At, B1); PG8_BAR; PG8_SCHED;
	s_add_i32 s14, s43, s23
	v_lshl_add_u64 v[178:179], v[178:179], 0, s[94:95]
	s_mov_b32 m0, s14
	ds_read_b128 v[210:213], v201 offset:49152
	ds_read_b128 v[214:217], v201 offset:50176
	ds_read_b128 v[218:221], v201 offset:51200
	ds_read_b128 v[222:225], v201 offset:52224
	ds_read_b128 v[226:229], v201 offset:53248
	ds_read_b128 v[230:233], v201 offset:54272
	ds_read_b128 v[234:237], v201 offset:55296
	ds_read_b128 v[238:241], v201 offset:56320
	global_load_lds_dwordx4 v[178:179], off
	v_lshl_add_u64 v[178:179], v[242:243], 0, s[94:95]
	s_add_i32 m0, s14, 0x2000
	s_add_i32 s14, s75, s23
	global_load_lds_dwordx4 v[178:179], off
	v_lshl_add_u64 v[178:179], v[244:245], 0, s[94:95]
	s_mov_b32 m0, s14
	s_nop 0
	global_load_lds_dwordx4 v[178:179], off
	v_lshl_add_u64 v[178:179], v[246:247], 0, s[94:95]
	s_add_i32 m0, s14, 0x2000
	s_nop 0
	global_load_lds_dwordx4 v[178:179], off
	v_lshl_add_u64 v[178:179], v[248:249], 0, s[94:95]
	s_mov_b32 m0, s63
	s_nop 0
	global_load_lds_dwordx4 v[178:179], off
	v_lshl_add_u64 v[178:179], v[250:251], 0, s[94:95]
	s_mov_b32 m0, s70
	s_nop 0
	global_load_lds_dwordx4 v[178:179], off
	s_waitcnt vmcnt(8)
	s_waitcnt lgkmcnt(0)
	s_barrier
	s_setprio 1
	s_waitcnt lgkmcnt(0)
	v_mfma_f32_16x16x32_bf16 v[62:65], v[130:133], v[210:213], v[62:65]
	v_mfma_f32_16x16x32_bf16 v[62:65], v[134:137], v[214:217], v[62:65]
	v_mfma_f32_16x16x32_bf16 v[58:61], v[138:141], v[210:213], v[58:61]
	v_mfma_f32_16x16x32_bf16 v[58:61], v[142:145], v[214:217], v[58:61]
	v_mfma_f32_16x16x32_bf16 v[46:49], v[130:133], v[218:221], v[46:49]
	v_mfma_f32_16x16x32_bf16 v[46:49], v[134:137], v[222:225], v[46:49]
	v_mfma_f32_16x16x32_bf16 v[42:45], v[138:141], v[218:221], v[42:45]
	v_mfma_f32_16x16x32_bf16 v[42:45], v[142:145], v[222:225], v[42:45]
	v_mfma_f32_16x16x32_bf16 v[30:33], v[130:133], v[226:229], v[30:33]
	v_mfma_f32_16x16x32_bf16 v[30:33], v[134:137], v[230:233], v[30:33]
	v_mfma_f32_16x16x32_bf16 v[26:29], v[138:141], v[226:229], v[26:29]
	v_mfma_f32_16x16x32_bf16 v[26:29], v[142:145], v[230:233], v[26:29]
	v_mfma_f32_16x16x32_bf16 v[14:17], v[130:133], v[234:237], v[14:17]
	v_mfma_f32_16x16x32_bf16 v[14:17], v[134:137], v[238:241], v[14:17]
	v_mfma_f32_16x16x32_bf16 v[10:13], v[138:141], v[234:237], v[10:13]
	v_mfma_f32_16x16x32_bf16 v[10:13], v[142:145], v[238:241], v[10:13]
	s_setprio 0
	s_setprio 1
	v_mfma_f32_16x16x32_bf16 v[54:57], v[170:173], v[210:213], v[54:57]
	v_mfma_f32_16x16x32_bf16 v[54:57], v[174:177], v[214:217], v[54:57]
	v_mfma_f32_16x16x32_bf16 v[50:53], v[202:205], v[210:213], v[50:53]
	v_mfma_f32_16x16x32_bf16 v[50:53], v[206:209], v[214:217], v[50:53]
	v_mfma_f32_16x16x32_bf16 v[38:41], v[170:173], v[218:221], v[38:41]
	v_mfma_f32_16x16x32_bf16 v[38:41], v[174:177], v[222:225], v[38:41]
	v_mfma_f32_16x16x32_bf16 v[34:37], v[202:205], v[218:221], v[34:37]
	v_mfma_f32_16x16x32_bf16 v[34:37], v[206:209], v[222:225], v[34:37]
	v_mfma_f32_16x16x32_bf16 v[22:25], v[170:173], v[226:229], v[22:25]
	v_mfma_f32_16x16x32_bf16 v[22:25], v[174:177], v[230:233], v[22:25]
	v_mfma_f32_16x16x32_bf16 v[18:21], v[202:205], v[226:229], v[18:21]
	v_mfma_f32_16x16x32_bf16 v[18:21], v[206:209], v[230:233], v[18:21]
	v_mfma_f32_16x16x32_bf16 v[6:9], v[170:173], v[234:237], v[6:9]
	v_mfma_f32_16x16x32_bf16 v[6:9], v[174:177], v[238:241], v[6:9]
	v_mfma_f32_16x16x32_bf16 v[2:5], v[202:205], v[234:237], v[2:5]
	v_mfma_f32_16x16x32_bf16 v[2:5], v[206:209], v[238:241], v[2:5]
	s_setprio 0
	s_barrier
	s_add_u32 s12, s12, 0x100
	s_addc_u32 s13, s13, 0
	s_add_u32 s16, s16, 0x100
	s_addc_u32 s17, s17, 0
	s_cmp_ge_u32 s42, s28
	s_mov_b32 s14, s42
	s_cbranch_scc0 .LBB0_322
	s_branch .Lk_done

; #define PG8_BAR __builtin_amdgcn_s_barrier()
;     __device__ __forceinline__ void operator()(const f32x4 (&acc)[2][2][4][2], const Unit& u, int wr, int wc, int fr, int fq) const {
;         if (mode == 0) { EpiQKV e{(bf16_t*)O, ldc, ntile_main, G}; e(acc, u, wr, wc, fr, fq); }
; template <class Epi, class Sched, bool ALIGN_EPI = false, bool SP2 = false>
; __device__ __forceinline__ void gemm_phase(PG8_LAS unsigned char* lds, const Gemm g, const Sched& S, const Epi& E) {
;     ...
;         if constexpr (ALIGN_EPI) { if (wr == 0) PG8_BAR; }
;         if constexpr (!Epi::AFTER_DRAIN) { E(acc, cur, wr, wc, fr, fq); S.done(cur); }
.Lk_done:
	s_and_b64 vcc, exec, s[48:49]
	s_cbranch_vccnz .LBB0_326
	v_lshl_add_u32 v170, s72, 8, v157
	s_cmp_lt_i32 s57, 1
	s_mov_b64 s[12:13], -1
	s_cbranch_scc0 .LBB0_327
